# v31: v30 + the down-GEMM epilogue row-sum shuffles as permlane swaps too (3-register form, 34 chains in all)
# baseline (speedup 1.0000x reference)
; __device__ __forceinline__ unsigned pkbf(float lo, float hi) { f32x2v v = {lo, hi}; bf16x2v b = __builtin_convertvector(v, bf16x2v); return __builtin_bit_cast(unsigned, b); }
;     __device__ __forceinline__ void operator()(const f32x4 (&acc)[2][2][4][2], const Unit& u, int wr, int wc, int fr, int fq) const {
;     ...
;                     if (Y) { float* yp = Y + (size_t)r * 4096 + col0 + bj * HALF; *(f32x4*)yp = a; *(f32x4*)(yp + 4) = b; }
;                     else {
;                         sq += (a[0] * a[0] + a[1] * a[1]) + (a[2] * a[2] + a[3] * a[3]) + (b[0] * b[0] + b[1] * b[1]) + (b[2] * b[2] + b[3] * b[3]);
;                         u32x4 w; w.x = pkbf(a[0], a[1]); w.y = pkbf(a[2], a[3]); w.z = pkbf(b[0], b[1]); w.w = pkbf(b[2], b[3]);
;                         *(u32x4*)(xp + bj * HALF) = w; } }
;                 if (!Y) { sq += __shfl_xor(sq, 16); sq += __shfl_xor(sq, 32); if (fq == 0) unsafeAtomicAdd(ssq + r, sq); }
.LBB0_3639:
	v_cndmask_b32_e64 v1, 0, 1, s[62:63]
	v_cmp_ne_u32_e64 s[46:47], 1, v1
	s_andn2_b64 vcc, exec, s[62:63]
	s_mov_b64 s[0:1], s[48:49]
	s_cbranch_vccnz .LBB0_3643
	v_and_b32_e32 v132, 64, v229
	v_xor_b32_e32 v1, 16, v229
	v_add_u32_e32 v133, 64, v132
	v_cmp_lt_i32_e32 vcc, v1, v133
	s_nop 1
	v_cndmask_b32_e32 v1, v229, v1, vcc
	v_lshlrev_b32_e32 v1, 2, v1
	v_mov_b32_e32 v1, v162
	v_mov_b32_e32 v132, v162
	s_nop 1
	v_permlane16_swap_b32_e32 v1, v132
	s_waitcnt lgkmcnt(0)
	v_add_f32_e32 v132, v132, v1
	v_xor_b32_e32 v1, 32, v229
	v_cmp_lt_i32_e32 vcc, v1, v133
	s_nop 1
	v_cndmask_b32_e32 v1, v229, v1, vcc
	v_lshlrev_b32_e32 v1, 2, v1
	v_mov_b32_e32 v133, v132
	s_nop 1
	v_permlane32_swap_b32_e32 v133, v132
	s_and_saveexec_b64 s[0:1], s[38:39]
	s_cbranch_execz .LBB0_3642
	v_lshl_add_u64 v[134:135], v[156:157], 2, s[60:61]
	s_waitcnt lgkmcnt(0)
	v_add_f32_e32 v1, v132, v133
	global_atomic_add_f32 v[134:135], v1, off

; __device__ __forceinline__ unsigned pkbf(float lo, float hi) { f32x2v v = {lo, hi}; bf16x2v b = __builtin_convertvector(v, bf16x2v); return __builtin_bit_cast(unsigned, b); }
;     __device__ __forceinline__ void operator()(const f32x4 (&acc)[2][2][4][2], const Unit& u, int wr, int wc, int fr, int fq) const {
;     ...
;                         sq += (a[0] * a[0] + a[1] * a[1]) + (a[2] * a[2] + a[3] * a[3]) + (b[0] * b[0] + b[1] * b[1]) + (b[2] * b[2] + b[3] * b[3]);
;                         u32x4 w; w.x = pkbf(a[0], a[1]); w.y = pkbf(a[2], a[3]); w.z = pkbf(b[0], b[1]); w.w = pkbf(b[2], b[3]);
;                         *(u32x4*)(xp + bj * HALF) = w; } }
;                 if (!Y) { sq += __shfl_xor(sq, 16); sq += __shfl_xor(sq, 32); if (fq == 0) unsafeAtomicAdd(ssq + r, sq); }
.LBB0_3654:
	v_and_b32_e32 v132, 64, v229
	v_xor_b32_e32 v1, 16, v229
	v_add_u32_e32 v133, 64, v132
	v_cmp_lt_i32_e32 vcc, v1, v133
	s_nop 1
	v_cndmask_b32_e32 v1, v229, v1, vcc
	v_lshlrev_b32_e32 v1, 2, v1
	v_mov_b32_e32 v1, v157
	v_mov_b32_e32 v132, v157
	s_nop 1
	v_permlane16_swap_b32_e32 v1, v132
	s_waitcnt lgkmcnt(0)
	v_add_f32_e32 v132, v132, v1
	v_xor_b32_e32 v1, 32, v229
	v_cmp_lt_i32_e32 vcc, v1, v133
	s_nop 1
	v_cndmask_b32_e32 v1, v229, v1, vcc
	v_lshlrev_b32_e32 v1, 2, v1
	v_mov_b32_e32 v133, v132
	s_nop 1
	v_permlane32_swap_b32_e32 v133, v132
	s_and_saveexec_b64 s[0:1], s[38:39]
	s_cbranch_execz .LBB0_3656
	v_lshl_add_u64 v[134:135], v[158:159], 2, s[60:61]
	s_waitcnt lgkmcnt(0)
	v_add_f32_e32 v1, v132, v133
	global_atomic_add_f32 v[134:135], v1, off

; __device__ __forceinline__ unsigned pkbf(float lo, float hi) { f32x2v v = {lo, hi}; bf16x2v b = __builtin_convertvector(v, bf16x2v); return __builtin_bit_cast(unsigned, b); }
;     __device__ __forceinline__ void operator()(const f32x4 (&acc)[2][2][4][2], const Unit& u, int wr, int wc, int fr, int fq) const {
;     ...
;                     if (Y) { float* yp = Y + (size_t)r * 4096 + col0 + bj * HALF; *(f32x4*)yp = a; *(f32x4*)(yp + 4) = b; }
;                     else {
;                         sq += (a[0] * a[0] + a[1] * a[1]) + (a[2] * a[2] + a[3] * a[3]) + (b[0] * b[0] + b[1] * b[1]) + (b[2] * b[2] + b[3] * b[3]);
;                         u32x4 w; w.x = pkbf(a[0], a[1]); w.y = pkbf(a[2], a[3]); w.z = pkbf(b[0], b[1]); w.w = pkbf(b[2], b[3]);
;                         *(u32x4*)(xp + bj * HALF) = w; } }
;                 if (!Y) { sq += __shfl_xor(sq, 16); sq += __shfl_xor(sq, 32); if (fq == 0) unsafeAtomicAdd(ssq + r, sq); }
.LBB0_3745:
	v_cndmask_b32_e64 v1, 0, 1, s[62:63]
	v_cmp_ne_u32_e64 s[46:47], 1, v1
	s_andn2_b64 vcc, exec, s[62:63]
	s_mov_b64 s[0:1], s[48:49]
	s_cbranch_vccnz .LBB0_3749
	v_and_b32_e32 v4, 64, v229
	v_xor_b32_e32 v1, 16, v229
	v_add_u32_e32 v5, 64, v4
	v_cmp_lt_i32_e32 vcc, v1, v5
	s_nop 1
	v_cndmask_b32_e32 v1, v229, v1, vcc
	v_lshlrev_b32_e32 v1, 2, v1
	v_mov_b32_e32 v1, v154
	v_mov_b32_e32 v4, v154
	s_nop 1
	v_permlane16_swap_b32_e32 v1, v4
	s_waitcnt lgkmcnt(0)
	v_add_f32_e32 v4, v4, v1
	v_xor_b32_e32 v1, 32, v229
	v_cmp_lt_i32_e32 vcc, v1, v5
	s_nop 1
	v_cndmask_b32_e32 v1, v229, v1, vcc
	v_lshlrev_b32_e32 v1, 2, v1
	v_mov_b32_e32 v5, v4
	s_nop 1
	v_permlane32_swap_b32_e32 v5, v4
	s_and_saveexec_b64 s[0:1], s[38:39]
	s_cbranch_execz .LBB0_3748
	v_lshl_add_u64 v[6:7], v[130:131], 2, s[60:61]
	s_waitcnt lgkmcnt(0)
	v_add_f32_e32 v1, v4, v5
	global_atomic_add_f32 v[6:7], v1, off

; __device__ __forceinline__ unsigned pkbf(float lo, float hi) { f32x2v v = {lo, hi}; bf16x2v b = __builtin_convertvector(v, bf16x2v); return __builtin_bit_cast(unsigned, b); }
;     __device__ __forceinline__ void operator()(const f32x4 (&acc)[2][2][4][2], const Unit& u, int wr, int wc, int fr, int fq) const {
;     ...
;                         sq += (a[0] * a[0] + a[1] * a[1]) + (a[2] * a[2] + a[3] * a[3]) + (b[0] * b[0] + b[1] * b[1]) + (b[2] * b[2] + b[3] * b[3]);
;                         u32x4 w; w.x = pkbf(a[0], a[1]); w.y = pkbf(a[2], a[3]); w.z = pkbf(b[0], b[1]); w.w = pkbf(b[2], b[3]);
;                         *(u32x4*)(xp + bj * HALF) = w; } }
;                 if (!Y) { sq += __shfl_xor(sq, 16); sq += __shfl_xor(sq, 32); if (fq == 0) unsafeAtomicAdd(ssq + r, sq); }
.LBB0_3757:
	v_and_b32_e32 v4, 64, v229
	v_xor_b32_e32 v1, 16, v229
	v_add_u32_e32 v5, 64, v4
	v_cmp_lt_i32_e32 vcc, v1, v5
	s_nop 1
	v_cndmask_b32_e32 v1, v229, v1, vcc
	v_lshlrev_b32_e32 v1, 2, v1
	v_mov_b32_e32 v1, v122
	v_mov_b32_e32 v4, v122
	s_nop 1
	v_permlane16_swap_b32_e32 v1, v4
	s_waitcnt lgkmcnt(0)
	v_add_f32_e32 v4, v4, v1
	v_xor_b32_e32 v1, 32, v229
	v_cmp_lt_i32_e32 vcc, v1, v5
	s_nop 1
	v_cndmask_b32_e32 v1, v229, v1, vcc
	v_lshlrev_b32_e32 v1, 2, v1
	v_mov_b32_e32 v5, v4
	s_nop 1
	v_permlane32_swap_b32_e32 v5, v4
	s_and_saveexec_b64 s[0:1], s[38:39]
	s_cbranch_execz .LBB0_3759
	v_lshl_add_u64 v[6:7], v[132:133], 2, s[60:61]
	s_waitcnt lgkmcnt(0)
	v_add_f32_e32 v1, v4, v5
	global_atomic_add_f32 v[6:7], v1, off

; __device__ __forceinline__ unsigned pkbf(float lo, float hi) { f32x2v v = {lo, hi}; bf16x2v b = __builtin_convertvector(v, bf16x2v); return __builtin_bit_cast(unsigned, b); }
;     __device__ __forceinline__ void operator()(const f32x4 (&acc)[2][2][4][2], const Unit& u, int wr, int wc, int fr, int fq) const {
;     ...
;                         sq += (a[0] * a[0] + a[1] * a[1]) + (a[2] * a[2] + a[3] * a[3]) + (b[0] * b[0] + b[1] * b[1]) + (b[2] * b[2] + b[3] * b[3]);
;                         u32x4 w; w.x = pkbf(a[0], a[1]); w.y = pkbf(a[2], a[3]); w.z = pkbf(b[0], b[1]); w.w = pkbf(b[2], b[3]);
;                         *(u32x4*)(xp + bj * HALF) = w; } }
;                 if (!Y) { sq += __shfl_xor(sq, 16); sq += __shfl_xor(sq, 32); if (fq == 0) unsafeAtomicAdd(ssq + r, sq); }
.LBB0_3768:
	v_and_b32_e32 v4, 64, v229
	v_xor_b32_e32 v1, 16, v229
	v_add_u32_e32 v5, 64, v4
	v_cmp_lt_i32_e32 vcc, v1, v5
	s_nop 1
	v_cndmask_b32_e32 v1, v229, v1, vcc
	v_lshlrev_b32_e32 v1, 2, v1
	v_mov_b32_e32 v1, v104
	v_mov_b32_e32 v4, v104
	s_nop 1
	v_permlane16_swap_b32_e32 v1, v4
	s_waitcnt lgkmcnt(0)
	v_add_f32_e32 v4, v4, v1
	v_xor_b32_e32 v1, 32, v229
	v_cmp_lt_i32_e32 vcc, v1, v5
	s_nop 1
	v_cndmask_b32_e32 v1, v229, v1, vcc
	v_lshlrev_b32_e32 v1, 2, v1
	v_mov_b32_e32 v5, v4
	s_nop 1
	v_permlane32_swap_b32_e32 v5, v4
	s_and_saveexec_b64 s[0:1], s[38:39]
	s_cbranch_execz .LBB0_3770
	v_lshl_add_u64 v[6:7], v[112:113], 2, s[60:61]
	s_waitcnt lgkmcnt(0)
	v_add_f32_e32 v1, v4, v5
	global_atomic_add_f32 v[6:7], v1, off

; __device__ __forceinline__ unsigned pkbf(float lo, float hi) { f32x2v v = {lo, hi}; bf16x2v b = __builtin_convertvector(v, bf16x2v); return __builtin_bit_cast(unsigned, b); }
;     __device__ __forceinline__ void operator()(const f32x4 (&acc)[2][2][4][2], const Unit& u, int wr, int wc, int fr, int fq) const {
;     ...
;                         sq += (a[0] * a[0] + a[1] * a[1]) + (a[2] * a[2] + a[3] * a[3]) + (b[0] * b[0] + b[1] * b[1]) + (b[2] * b[2] + b[3] * b[3]);
;                         u32x4 w; w.x = pkbf(a[0], a[1]); w.y = pkbf(a[2], a[3]); w.z = pkbf(b[0], b[1]); w.w = pkbf(b[2], b[3]);
;                         *(u32x4*)(xp + bj * HALF) = w; } }
;                 if (!Y) { sq += __shfl_xor(sq, 16); sq += __shfl_xor(sq, 32); if (fq == 0) unsafeAtomicAdd(ssq + r, sq); }
.LBB0_3779:
	v_and_b32_e32 v4, 64, v229
	v_xor_b32_e32 v1, 16, v229
	v_add_u32_e32 v5, 64, v4
	v_cmp_lt_i32_e32 vcc, v1, v5
	s_nop 1
	v_cndmask_b32_e32 v1, v229, v1, vcc
	v_lshlrev_b32_e32 v1, 2, v1
	v_mov_b32_e32 v1, v88
	v_mov_b32_e32 v4, v88
	s_nop 1
	v_permlane16_swap_b32_e32 v1, v4
	s_waitcnt lgkmcnt(0)
	v_add_f32_e32 v4, v4, v1
	v_xor_b32_e32 v1, 32, v229
	v_cmp_lt_i32_e32 vcc, v1, v5
	s_nop 1
	v_cndmask_b32_e32 v1, v229, v1, vcc
	v_lshlrev_b32_e32 v1, 2, v1
	v_mov_b32_e32 v5, v4
	s_nop 1
	v_permlane32_swap_b32_e32 v5, v4
	s_and_saveexec_b64 s[0:1], s[38:39]
	s_cbranch_execz .LBB0_3781
	v_lshl_add_u64 v[6:7], v[96:97], 2, s[60:61]
	s_waitcnt lgkmcnt(0)
	v_add_f32_e32 v1, v4, v5
	global_atomic_add_f32 v[6:7], v1, off

; __device__ __forceinline__ unsigned pkbf(float lo, float hi) { f32x2v v = {lo, hi}; bf16x2v b = __builtin_convertvector(v, bf16x2v); return __builtin_bit_cast(unsigned, b); }
;     __device__ __forceinline__ void operator()(const f32x4 (&acc)[2][2][4][2], const Unit& u, int wr, int wc, int fr, int fq) const {
;     ...
;                         sq += (a[0] * a[0] + a[1] * a[1]) + (a[2] * a[2] + a[3] * a[3]) + (b[0] * b[0] + b[1] * b[1]) + (b[2] * b[2] + b[3] * b[3]);
;                         u32x4 w; w.x = pkbf(a[0], a[1]); w.y = pkbf(a[2], a[3]); w.z = pkbf(b[0], b[1]); w.w = pkbf(b[2], b[3]);
;                         *(u32x4*)(xp + bj * HALF) = w; } }
;                 if (!Y) { sq += __shfl_xor(sq, 16); sq += __shfl_xor(sq, 32); if (fq == 0) unsafeAtomicAdd(ssq + r, sq); }
.LBB0_3790:
	v_and_b32_e32 v4, 64, v229
	v_xor_b32_e32 v1, 16, v229
	v_add_u32_e32 v5, 64, v4
	v_cmp_lt_i32_e32 vcc, v1, v5
	s_nop 1
	v_cndmask_b32_e32 v1, v229, v1, vcc
	v_lshlrev_b32_e32 v1, 2, v1
	v_mov_b32_e32 v1, v72
	v_mov_b32_e32 v4, v72
	s_nop 1
	v_permlane16_swap_b32_e32 v1, v4
	s_waitcnt lgkmcnt(0)
	v_add_f32_e32 v4, v4, v1
	v_xor_b32_e32 v1, 32, v229
	v_cmp_lt_i32_e32 vcc, v1, v5
	s_nop 1
	v_cndmask_b32_e32 v1, v229, v1, vcc
	v_lshlrev_b32_e32 v1, 2, v1
	v_mov_b32_e32 v5, v4
	s_nop 1
	v_permlane32_swap_b32_e32 v5, v4
	s_and_saveexec_b64 s[0:1], s[38:39]
	s_cbranch_execz .LBB0_3792
	v_lshl_add_u64 v[6:7], v[80:81], 2, s[60:61]
	s_waitcnt lgkmcnt(0)
	v_add_f32_e32 v1, v4, v5
	global_atomic_add_f32 v[6:7], v1, off

; __device__ __forceinline__ unsigned pkbf(float lo, float hi) { f32x2v v = {lo, hi}; bf16x2v b = __builtin_convertvector(v, bf16x2v); return __builtin_bit_cast(unsigned, b); }
;     __device__ __forceinline__ void operator()(const f32x4 (&acc)[2][2][4][2], const Unit& u, int wr, int wc, int fr, int fq) const {
;     ...
;                         sq += (a[0] * a[0] + a[1] * a[1]) + (a[2] * a[2] + a[3] * a[3]) + (b[0] * b[0] + b[1] * b[1]) + (b[2] * b[2] + b[3] * b[3]);
;                         u32x4 w; w.x = pkbf(a[0], a[1]); w.y = pkbf(a[2], a[3]); w.z = pkbf(b[0], b[1]); w.w = pkbf(b[2], b[3]);
;                         *(u32x4*)(xp + bj * HALF) = w; } }
;                 if (!Y) { sq += __shfl_xor(sq, 16); sq += __shfl_xor(sq, 32); if (fq == 0) unsafeAtomicAdd(ssq + r, sq); }
.LBB0_3801:
	v_and_b32_e32 v4, 64, v229
	v_xor_b32_e32 v1, 16, v229
	v_add_u32_e32 v5, 64, v4
	v_cmp_lt_i32_e32 vcc, v1, v5
	s_nop 1
	v_cndmask_b32_e32 v1, v229, v1, vcc
	v_lshlrev_b32_e32 v1, 2, v1
	v_mov_b32_e32 v1, v56
	v_mov_b32_e32 v4, v56
	s_nop 1
	v_permlane16_swap_b32_e32 v1, v4
	s_waitcnt lgkmcnt(0)
	v_add_f32_e32 v4, v4, v1
	v_xor_b32_e32 v1, 32, v229
	v_cmp_lt_i32_e32 vcc, v1, v5
	s_nop 1
	v_cndmask_b32_e32 v1, v229, v1, vcc
	v_lshlrev_b32_e32 v1, 2, v1
	v_mov_b32_e32 v5, v4
	s_nop 1
	v_permlane32_swap_b32_e32 v5, v4
	s_and_saveexec_b64 s[0:1], s[38:39]
	s_cbranch_execz .LBB0_3803
	v_lshl_add_u64 v[6:7], v[64:65], 2, s[60:61]
	s_waitcnt lgkmcnt(0)
	v_add_f32_e32 v1, v4, v5
	global_atomic_add_f32 v[6:7], v1, off

; __device__ __forceinline__ unsigned pkbf(float lo, float hi) { f32x2v v = {lo, hi}; bf16x2v b = __builtin_convertvector(v, bf16x2v); return __builtin_bit_cast(unsigned, b); }
;     __device__ __forceinline__ void operator()(const f32x4 (&acc)[2][2][4][2], const Unit& u, int wr, int wc, int fr, int fq) const {
;     ...
;                         sq += (a[0] * a[0] + a[1] * a[1]) + (a[2] * a[2] + a[3] * a[3]) + (b[0] * b[0] + b[1] * b[1]) + (b[2] * b[2] + b[3] * b[3]);
;                         u32x4 w; w.x = pkbf(a[0], a[1]); w.y = pkbf(a[2], a[3]); w.z = pkbf(b[0], b[1]); w.w = pkbf(b[2], b[3]);
;                         *(u32x4*)(xp + bj * HALF) = w; } }
;                 if (!Y) { sq += __shfl_xor(sq, 16); sq += __shfl_xor(sq, 32); if (fq == 0) unsafeAtomicAdd(ssq + r, sq); }
.LBB0_3812:
	v_and_b32_e32 v4, 64, v229
	v_xor_b32_e32 v1, 16, v229
	v_add_u32_e32 v5, 64, v4
	v_cmp_lt_i32_e32 vcc, v1, v5
	s_nop 1
	v_cndmask_b32_e32 v1, v229, v1, vcc
	v_lshlrev_b32_e32 v1, 2, v1
	v_mov_b32_e32 v1, v40
	v_mov_b32_e32 v4, v40
	s_nop 1
	v_permlane16_swap_b32_e32 v1, v4
	s_waitcnt lgkmcnt(0)
	v_add_f32_e32 v4, v4, v1
	v_xor_b32_e32 v1, 32, v229
	v_cmp_lt_i32_e32 vcc, v1, v5
	s_nop 1
	v_cndmask_b32_e32 v1, v229, v1, vcc
	v_lshlrev_b32_e32 v1, 2, v1
	v_mov_b32_e32 v5, v4
	s_nop 1
	v_permlane32_swap_b32_e32 v5, v4
	s_and_saveexec_b64 s[0:1], s[38:39]
	s_cbranch_execz .LBB0_3814
	v_lshl_add_u64 v[6:7], v[48:49], 2, s[60:61]
	s_waitcnt lgkmcnt(0)
	v_add_f32_e32 v1, v4, v5
	global_atomic_add_f32 v[6:7], v1, off
